# LDS bank conflicts: long-conv filter copies placed at 96-slot stride plus per-copy offsets, conflict-free A-operand ds_read_b128
# speedup vs baseline: 1.0060x; 1.0016x over previous
; __device__ __forceinline__ void toeplitz_item(const Params& p, int layer, int half, int c, bf16* sm, int dry, unsigned* done_ctr) {
;     ...
;   const int aq = (8 - (r & 7)) & 7;
;   const int rt = (r + 7) >> 3;
;   bf16 wreg[3];
;   {
;     const int m0 = OFF - 128 * (-nb + 3) - 128;
; #pragma unroll
;     for (int i = 0; i < 3; ++i) { int x = tid + 256 * i; wreg[i] = x < 648 ? rho[m0 + x] : (bf16)0; }
;   }
;   for (int bt = 0; bt < nbatch; ++bt) {
;     const int D0 = -nb + 4 * bt;
;     __syncthreads();
; #pragma unroll
;     for (int i = 0; i < 3; ++i) {
;       const int x = tid + 256 * i;
;       if (x < 648) {
; #pragma unroll
;         for (int qq = 0; qq < 8; ++qq) {
;           const int y = x - qq;
;           if (y >= 0 && (y >> 3) < 80) sW[(qq * 83 + (y >> 3)) * 8 + (y & 7)] = wreg[i];
;         }
;       }
;     }
.LBB0_1146:
	s_or_b64 exec, exec, s[22:23]
	v_add_u32_e32 v10, -1, v4
	s_movk_i32 s40, 0x280
	v_and_b32_e32 v11, 7, v10
	v_cmp_gt_u32_e64 s[90:91], s40, v10
	v_add_u32_e32 v10, 0x297, v4
	v_and_b32_e32 v10, 0x7f8, v10
	v_lshlrev_b32_e32 v11, 1, v11
	v_add_u32_e32 v12, 6, v4
	v_lshl_or_b32 v119, v10, 1, v11
	v_add_u32_e32 v10, -2, v4
	v_and_b32_e32 v12, 7, v12
	v_cmp_gt_u32_e64 s[88:89], s40, v10
	v_add_u32_e32 v10, 0x52e, v4
	v_and_b32_e32 v10, 0xff8, v10
	v_lshlrev_b32_e32 v12, 1, v12
	v_add_u32_e32 v13, 5, v4
	v_lshl_or_b32 v118, v10, 1, v12
	v_add_u32_e32 v10, -3, v4
	v_and_b32_e32 v13, 7, v13
	v_cmp_gt_u32_e64 s[86:87], s40, v10
	v_add_u32_e32 v10, 0x7c5, v4
	v_and_b32_e32 v10, 0xff8, v10
	v_lshlrev_b32_e32 v13, 1, v13
	v_lshl_or_b32 v117, v10, 1, v13
	v_add_u32_e32 v10, -4, v4
	v_bitop3_b32 v15, v4, 4, 7 bitop3:0x6c
	v_cmp_gt_u32_e64 s[84:85], s40, v10
	v_add_u32_e32 v10, 0xa5c, v4
	v_and_b32_e32 v10, 0xff8, v10
	v_lshlrev_b32_e32 v15, 1, v15
	v_add_u32_e32 v16, 3, v4
	v_lshl_or_b32 v116, v10, 1, v15
	v_add_u32_e32 v10, -5, v4
	v_and_b32_e32 v16, 7, v16
	v_cmp_gt_u32_e64 s[82:83], s40, v10
	v_add_u32_e32 v10, 0xcf3, v4
	v_and_b32_e32 v10, 0x1ff8, v10
	v_lshlrev_b32_e32 v16, 1, v16
	v_add_u32_e32 v17, 2, v4
	v_lshl_or_b32 v115, v10, 1, v16
	v_add_u32_e32 v10, -6, v4
	v_and_b32_e32 v17, 7, v17
	v_cmp_gt_u32_e64 s[80:81], s40, v10
	v_add_u32_e32 v10, 0xf8a, v4
	v_and_b32_e32 v10, 0x1ff8, v10
	v_lshlrev_b32_e32 v17, 1, v17
	v_add_u32_e32 v18, 1, v4
	v_lshl_or_b32 v114, v10, 1, v17
	v_add_u32_e32 v10, -7, v4
	v_and_b32_e32 v18, 7, v18
	v_cmp_gt_u32_e64 s[78:79], s40, v10
	v_add_u32_e32 v10, 0x1221, v4
	v_add_u32_e32 v8, 0x100, v4
	v_and_b32_e32 v14, 7, v4
	v_and_b32_e32 v10, 0x17f8, v10
	v_lshlrev_b32_e32 v18, 1, v18
	v_lshlrev_b32_e32 v14, 1, v14
	v_lshl_or_b32 v113, v10, 1, v18
	v_and_b32_e32 v10, 0x3f8, v8
	v_lshl_or_b32 v112, v10, 1, v14
	v_add_u32_e32 v10, 0xff, v4
	v_cmp_gt_u32_e64 s[38:39], s40, v10
	v_add_u32_e32 v10, 0x397, v4
	v_and_b32_e32 v10, 0x3ff8, v10
	v_lshl_or_b32 v111, v10, 1, v11
	v_add_u32_e32 v10, 0xfe, v4
	v_cmp_gt_u32_e64 s[36:37], s40, v10
	v_add_u32_e32 v10, 0x62e, v4
	v_and_b32_e32 v10, 0x3ff8, v10
	v_lshl_or_b32 v110, v10, 1, v12
	v_add_u32_e32 v10, 0xfd, v4
	v_cmp_gt_u32_e64 s[34:35], s40, v10
	v_add_u32_e32 v10, 0x8c5, v4
	v_and_b32_e32 v10, 0x3ff8, v10
	v_lshl_or_b32 v109, v10, 1, v13
	v_add_u32_e32 v10, 0xfc, v4
	v_cmp_gt_u32_e64 s[30:31], s40, v10
	v_add_u32_e32 v10, 0xb5c, v4
	v_and_b32_e32 v10, 0x3ff8, v10
	v_lshl_or_b32 v108, v10, 1, v15
	v_add_u32_e32 v10, 0xfb, v4
	v_cmp_gt_u32_e64 s[28:29], s40, v10
	v_add_u32_e32 v10, 0xdf3, v4
	v_and_b32_e32 v10, 0x3ff8, v10
	v_lshl_or_b32 v107, v10, 1, v16
	v_add_u32_e32 v10, 0xfa, v4
	v_cmp_gt_u32_e64 s[26:27], s40, v10
	v_add_u32_e32 v10, 0x108a, v4
	v_and_b32_e32 v10, 0x3ff8, v10
	v_lshl_or_b32 v106, v10, 1, v17
	v_add_u32_e32 v10, 0xf9, v4
	v_cmp_gt_u32_e64 s[24:25], s40, v10
	v_add_u32_e32 v10, 0x1321, v4
	v_and_b32_e32 v10, 0x3ff8, v10
	v_lshl_or_b32 v105, v10, 1, v18
	v_and_b32_e32 v10, 0x3f8, v6
	v_lshl_or_b32 v104, v10, 1, v14
	v_add_u32_e32 v10, 0x1ff, v4
	v_cmp_gt_u32_e64 s[58:59], s40, v10
	v_add_u32_e32 v10, 0x497, v4
	v_and_b32_e32 v10, 0x3ff8, v10
	v_lshl_or_b32 v103, v10, 1, v11
	v_add_u32_e32 v10, 0x1fe, v4
	v_cmp_gt_u32_e64 s[56:57], s40, v10
	v_add_u32_e32 v10, 0x72e, v4
	v_and_b32_e32 v10, 0x3ff8, v10
	v_lshl_or_b32 v102, v10, 1, v12
	v_add_u32_e32 v10, 0x1fd, v4
	v_cmp_gt_u32_e64 s[96:97], s40, v10
	v_add_u32_e32 v10, 0x9c5, v4
	v_and_b32_e32 v10, 0x3ff8, v10
	v_lshl_or_b32 v101, v10, 1, v13
	v_add_u32_e32 v10, 0x1fc, v4
	v_cmp_gt_u32_e64 s[94:95], s40, v10
	v_add_u32_e32 v10, 0xc5c, v4
	v_and_b32_e32 v10, 0x3ff8, v10
	v_lshl_or_b32 v100, v10, 1, v15
	v_add_u32_e32 v10, 0x1fb, v4
; __device__ __forceinline__ void toeplitz_item(const Params& p, int layer, int half, int c, bf16* sm, int dry, unsigned* done_ctr) {
;     ...
;   const int aq = (8 - (r & 7)) & 7;
;   const int rt = (r + 7) >> 3;
;   bf16 wreg[3];
;   {
;     const int m0 = OFF - 128 * (-nb + 3) - 128;
; #pragma unroll
;     for (int i = 0; i < 3; ++i) { int x = tid + 256 * i; wreg[i] = x < 648 ? rho[m0 + x] : (bf16)0; }
;   }
;   for (int bt = 0; bt < nbatch; ++bt) {
;     const int D0 = -nb + 4 * bt;
;     __syncthreads();
; #pragma unroll
;     for (int i = 0; i < 3; ++i) {
;       const int x = tid + 256 * i;
;       if (x < 648) {
; #pragma unroll
;         for (int qq = 0; qq < 8; ++qq) {
;           const int y = x - qq;
;           if (y >= 0 && (y >> 3) < 80) sW[(qq * 83 + (y >> 3)) * 8 + (y & 7)] = wreg[i];
;         }
;       }
;     }
;     __syncthreads();
;     if (bt + 1 < nbatch) {
;       const int m0 = OFF - 128 * (D0 + 4 + 3) - 128;
; #pragma unroll
;       for (int i = 0; i < 3; ++i) { int x = tid + 256 * i; wreg[i] = x < 648 ? rho[m0 + x] : (bf16)0; }
;     }
;     for (int Dl = 0; Dl < 4; ++Dl) {
;       const int D = D0 + Dl;
;       bool actv[2];
;       int bblk[2];
; #pragma unroll
;       for (int ni = 0; ni < 2; ++ni) {
;         const int nlo = 32 * wn + 64 * ni;
;         actv[ni] = half ? true : !((nlo + 31 - D < 0) || (nlo - D >= 128));
;         const int n = nlo + r;
;         const int src = n - D;
;         const bool valid = half ? ((unsigned)((n & 15) - D) < 16u) : ((unsigned)src < 128u);
;         bblk[ni] = valid ? src : 128;
;       }
;       if (!actv[0] && !actv[1]) continue;
;       const int tb = 16 * (3 - Dl) + 16 + hh - rt;
;       const bf16* ap0 = sW + (aq * 83 + tb - 4 * (2 * wm)) * 8;
;       const bf16* bp0 = sU + bblk[0] * 136 + 8 * hh;
;       const bf16* bp1 = sU + bblk[1] * 136 + 8 * hh;
	v_cmp_gt_u32_e64 s[70:71], s40, v10
	v_add_u32_e32 v10, 0xef3, v4
	v_and_b32_e32 v10, 0x3ff8, v10
	v_lshl_or_b32 v99, v10, 1, v16
	v_add_u32_e32 v10, 0x1fa, v4
	v_cmp_gt_u32_e64 s[66:67], s40, v10
	v_add_u32_e32 v10, 0x118a, v4
	v_and_b32_e32 v94, 31, v4
	v_and_b32_e32 v10, 0x3ff8, v10
	v_sub_u32_e32 v3, 0, v4
	v_add_u32_e32 v9, 7, v94
	v_lshl_or_b32 v98, v10, 1, v17
	v_add_u32_e32 v10, 0x1f9, v4
	v_lshrrev_b32_e32 v0, 5, v0
	v_ashrrev_i32_e32 v88, 7, v4
	v_and_b32_e32 v3, 7, v3
	v_lshrrev_b32_e32 v9, 3, v9
	v_cmp_gt_u32_e32 vcc, s40, v4
	v_cmp_gt_u32_e64 s[20:21], s40, v8
	v_cmp_gt_u32_e64 s[22:23], s40, v6
	v_cmp_gt_u32_e64 s[64:65], s40, v10
	s_movk_i32 s40, 0x60
	v_lshlrev_b32_e32 v60, 2, v3
	v_mov_b32_e32 v61, 0x5d959d10
	v_lshrrev_b32_e32 v60, v60, v61
	v_and_b32_e32 v60, 15, v60
	v_add_u32_e32 v10, 0x1421, v4
	v_mad_u32_u24 v3, v3, s40, v0
	v_add_u32_e32 v3, v3, v60
	v_lshl_or_b32 v9, v88, 3, v9
	v_and_b32_e32 v10, 0x3ff8, v10
	v_sub_u32_e32 v3, v3, v9
	v_mov_b32_e32 v9, 0x400
	v_lshl_or_b32 v97, v10, 1, v18
	v_lshl_add_u32 v89, v3, 4, v9
	v_bfe_u32 v3, v4, 6, 1
	v_mul_u32_u24_e32 v10, 0x110, v94
	s_movk_i32 s40, 0x2200
	v_mad_u32_u24 v122, v3, s40, v10
	v_readlane_b32 s40, v254, 17
	s_add_u32 s2, s40, s2
	v_readlane_b32 s40, v254, 34
	v_and_b32_e32 v91, 15, v4
	v_and_b32_e32 v19, 0x3f8, v4
	v_ashrrev_i32_e32 v9, 31, v8
	s_addc_u32 s3, s40, s3
	s_mov_b32 s74, 0
	v_lshlrev_b32_e32 v90, 4, v0
	v_lshl_or_b32 v120, v19, 1, v14
	v_add_u32_e32 v123, 13, v91
	v_lshl_add_u64 v[82:83], v[6:7], 1, s[2:3]
	v_lshl_add_u64 v[84:85], v[8:9], 1, s[2:3]
	v_lshl_add_u64 v[86:87], v[4:5], 1, s[2:3]
	v_mov_b32_e32 v3, v2
	v_mov_b32_e32 v4, v2
	v_mov_b32_e32 v5, v2
	v_mov_b32_e32 v6, v2
	v_mov_b32_e32 v7, v2
	v_mov_b32_e32 v8, v2
	v_mov_b32_e32 v9, v2
	v_mov_b32_e32 v10, v2
	v_mov_b32_e32 v11, v2
	v_mov_b32_e32 v12, v2
	v_mov_b32_e32 v13, v2
	v_mov_b32_e32 v14, v2
	v_mov_b32_e32 v15, v2
	v_mov_b32_e32 v16, v2
	v_mov_b32_e32 v17, v2
	v_mov_b32_e32 v18, v2
	v_mov_b32_e32 v19, v2
	v_mov_b32_e32 v20, v2
	v_mov_b32_e32 v21, v2
	v_mov_b32_e32 v22, v2
	v_mov_b32_e32 v23, v2
	v_mov_b32_e32 v24, v2
	v_mov_b32_e32 v25, v2
	v_mov_b32_e32 v26, v2
	v_mov_b32_e32 v27, v2
	v_mov_b32_e32 v28, v2
	v_mov_b32_e32 v29, v2
	v_mov_b32_e32 v30, v2
	v_mov_b32_e32 v31, v2
	v_mov_b32_e32 v32, v2
	v_mov_b32_e32 v33, v2
	v_mov_b32_e32 v34, v2
	v_mov_b32_e32 v35, v2
	v_mov_b32_e32 v36, v2
	v_mov_b32_e32 v37, v2
	v_mov_b32_e32 v38, v2
	v_mov_b32_e32 v39, v2
	v_mov_b32_e32 v40, v2
	v_mov_b32_e32 v41, v2
	v_mov_b32_e32 v42, v2
	v_mov_b32_e32 v43, v2
	v_mov_b32_e32 v44, v2
	v_mov_b32_e32 v45, v2
	v_mov_b32_e32 v46, v2
	v_mov_b32_e32 v47, v2
	v_mov_b32_e32 v48, v2
	v_mov_b32_e32 v49, v2
	v_mov_b32_e32 v50, v2
	v_mov_b32_e32 v51, v2
	v_mov_b32_e32 v52, v2
	v_mov_b32_e32 v53, v2
	v_mov_b32_e32 v54, v2
	v_mov_b32_e32 v55, v2
	v_mov_b32_e32 v56, v2
	v_mov_b32_e32 v57, v2
	v_mov_b32_e32 v58, v2
	v_mov_b32_e32 v59, v2
	v_mov_b32_e32 v60, v2
	v_mov_b32_e32 v61, v2
	v_mov_b32_e32 v62, v2
	v_mov_b32_e32 v63, v2
	v_mov_b32_e32 v64, v2
	v_mov_b32_e32 v65, v2
	v_add_u32_e32 v119, 224, v119
	v_add_u32_e32 v118, 624, v118
	v_add_u32_e32 v117, 768, v117
	v_add_u32_e32 v116, 912, v116
	v_add_u32_e32 v115, 1184, v115
	v_add_u32_e32 v114, 1456, v114
	v_add_u32_e32 v113, 1536, v113
	v_add_u32_e32 v111, 224, v111
	v_add_u32_e32 v110, 624, v110
	v_add_u32_e32 v109, 768, v109
	v_add_u32_e32 v108, 912, v108
	v_add_u32_e32 v107, 1184, v107
	v_add_u32_e32 v106, 1456, v106
	v_add_u32_e32 v105, 1536, v105
	v_add_u32_e32 v103, 224, v103
	v_add_u32_e32 v102, 624, v102
	v_add_u32_e32 v101, 768, v101
	v_add_u32_e32 v100, 912, v100
	v_add_u32_e32 v99, 1184, v99
	v_add_u32_e32 v98, 1456, v98
	v_add_u32_e32 v97, 1536, v97
	s_branch .LBB0_1148

; __device__ __forceinline__ void toeplitz_item(const Params& p, int layer, int half, int c, bf16* sm, int dry, unsigned* done_ctr) {
;     ...
;   const int aq = (8 - (r & 7)) & 7;
;   const int rt = (r + 7) >> 3;
;   bf16 wreg[3];
;   {
;     const int m0 = OFF - 128 * (-nb + 3) - 128;
; #pragma unroll
;     for (int i = 0; i < 3; ++i) { int x = tid + 256 * i; wreg[i] = x < 648 ? rho[m0 + x] : (bf16)0; }
;   }
;   for (int bt = 0; bt < nbatch; ++bt) {
;     const int D0 = -nb + 4 * bt;
;     __syncthreads();
; #pragma unroll
;     for (int i = 0; i < 3; ++i) {
;       const int x = tid + 256 * i;
;       if (x < 648) {
; #pragma unroll
;         for (int qq = 0; qq < 8; ++qq) {
;           const int y = x - qq;
;           if (y >= 0 && (y >> 3) < 80) sW[(qq * 83 + (y >> 3)) * 8 + (y & 7)] = wreg[i];
;         }
;       }
;     }
.LBB0_1368:
	s_or_b64 exec, exec, s[2:3]
	v_add_u32_e32 v3, 0x200, v2
	v_and_b32_e32 v5, 31, v2
	v_and_b32_e32 v12, 7, v2
	s_movk_i32 s2, 0x280
	v_add_u32_e32 v4, 0x100, v2
	v_sub_u32_e32 v7, 0, v2
	v_add_u32_e32 v8, 7, v5
	v_lshlrev_b32_e32 v12, 1, v12
	v_cmp_gt_u32_e64 s[22:23], s2, v3
	v_and_b32_e32 v3, 0x3f8, v3
	v_lshrrev_b32_e32 v103, 5, v6
	v_and_b32_e32 v6, 7, v7
	v_lshrrev_b32_e32 v7, 3, v8
	v_add_u32_e32 v8, -1, v2
	v_cmp_gt_u32_e64 s[46:47], s2, v4
	v_and_b32_e32 v4, 0x3f8, v4
	v_lshl_or_b32 v118, v3, 1, v12
	v_add_u32_e32 v3, 0x1ff, v2
	v_and_b32_e32 v9, 7, v8
	v_lshl_or_b32 v126, v4, 1, v12
	v_add_u32_e32 v4, 0xff, v2
	v_cmp_gt_u32_e64 s[20:21], s2, v3
	v_add_u32_e32 v3, 0x497, v2
	v_cmp_gt_u32_e64 s[90:91], s2, v8
	v_add_u32_e32 v8, 0x297, v2
	v_lshlrev_b32_e32 v9, 1, v9
	v_cmp_gt_u32_e64 s[38:39], s2, v4
	v_add_u32_e32 v4, 0x397, v2
	v_and_b32_e32 v3, 0x3ff8, v3
	v_add_u32_e32 v10, 6, v2
	v_and_b32_e32 v8, 0x7f8, v8
	v_and_b32_e32 v4, 0x3ff8, v4
	v_writelane_b32 v255, s20, 20
	v_lshl_or_b32 v117, v3, 1, v9
	v_add_u32_e32 v3, 0x1fe, v2
	v_and_b32_e32 v10, 7, v10
	v_lshl_or_b32 v133, v8, 1, v9
	v_add_u32_e32 v8, -2, v2
	v_lshl_or_b32 v125, v4, 1, v9
	v_add_u32_e32 v4, 0xfe, v2
	v_writelane_b32 v255, s21, 21
	v_cmp_gt_u32_e64 s[20:21], s2, v3
	v_add_u32_e32 v3, 0x72e, v2
	v_cmp_gt_u32_e64 s[88:89], s2, v8
	v_add_u32_e32 v8, 0x52e, v2
	v_lshlrev_b32_e32 v10, 1, v10
	v_cmp_gt_u32_e64 s[36:37], s2, v4
	v_add_u32_e32 v4, 0x62e, v2
	v_and_b32_e32 v3, 0x3ff8, v3
	v_add_u32_e32 v11, 5, v2
	v_and_b32_e32 v8, 0xff8, v8
	v_and_b32_e32 v4, 0x3ff8, v4
	v_writelane_b32 v255, s20, 22
	v_lshl_or_b32 v116, v3, 1, v10
	v_add_u32_e32 v3, 0x1fd, v2
	v_and_b32_e32 v11, 7, v11
	v_lshl_or_b32 v132, v8, 1, v10
	v_add_u32_e32 v8, -3, v2
	v_lshl_or_b32 v124, v4, 1, v10
	v_add_u32_e32 v4, 0xfd, v2
	v_writelane_b32 v255, s21, 23
	v_cmp_gt_u32_e64 s[20:21], s2, v3
	v_add_u32_e32 v3, 0x9c5, v2
	v_cmp_gt_u32_e64 s[86:87], s2, v8
	v_add_u32_e32 v8, 0x7c5, v2
	v_lshlrev_b32_e32 v11, 1, v11
	v_cmp_gt_u32_e64 s[34:35], s2, v4
	v_add_u32_e32 v4, 0x8c5, v2
	v_and_b32_e32 v3, 0x3ff8, v3
	v_and_b32_e32 v8, 0xff8, v8
	v_and_b32_e32 v4, 0x3ff8, v4
	v_lshl_or_b32 v115, v3, 1, v11
	v_add_u32_e32 v3, 0x1fc, v2
	v_bitop3_b32 v13, v2, 4, 7 bitop3:0x6c
	v_lshl_or_b32 v131, v8, 1, v11
	v_add_u32_e32 v8, -4, v2
	v_lshl_or_b32 v123, v4, 1, v11
	v_add_u32_e32 v4, 0xfc, v2
	v_cmp_gt_u32_e64 s[76:77], s2, v3
	v_add_u32_e32 v3, 0xc5c, v2
	v_cmp_gt_u32_e64 s[84:85], s2, v8
	v_add_u32_e32 v8, 0xa5c, v2
	v_lshlrev_b32_e32 v13, 1, v13
	v_cmp_gt_u32_e64 s[30:31], s2, v4
	v_add_u32_e32 v4, 0xb5c, v2
	v_and_b32_e32 v3, 0x3ff8, v3
	v_add_u32_e32 v14, 3, v2
	v_and_b32_e32 v8, 0xff8, v8
	v_and_b32_e32 v4, 0x3ff8, v4
	v_lshl_or_b32 v114, v3, 1, v13
	v_add_u32_e32 v3, 0x1fb, v2
	v_and_b32_e32 v14, 7, v14
	v_lshl_or_b32 v130, v8, 1, v13
	v_add_u32_e32 v8, -5, v2
	v_lshl_or_b32 v122, v4, 1, v13
	v_add_u32_e32 v4, 0xfb, v2
	v_cmp_gt_u32_e64 s[72:73], s2, v3
	v_add_u32_e32 v3, 0xef3, v2
	v_cmp_gt_u32_e64 s[82:83], s2, v8
	v_add_u32_e32 v8, 0xcf3, v2
	v_lshlrev_b32_e32 v14, 1, v14
	v_cmp_gt_u32_e64 s[28:29], s2, v4
	v_add_u32_e32 v4, 0xdf3, v2
	v_and_b32_e32 v3, 0x3ff8, v3
	v_add_u32_e32 v15, 2, v2
	v_and_b32_e32 v8, 0x1ff8, v8
	v_and_b32_e32 v4, 0x3ff8, v4
	v_lshl_or_b32 v113, v3, 1, v14
	v_add_u32_e32 v3, 0x1fa, v2
	v_and_b32_e32 v15, 7, v15
	v_lshl_or_b32 v129, v8, 1, v14
	v_add_u32_e32 v8, -6, v2
	v_lshl_or_b32 v121, v4, 1, v14
	v_add_u32_e32 v4, 0xfa, v2
	v_cmp_gt_u32_e64 s[66:67], s2, v3
	v_add_u32_e32 v3, 0x118a, v2
	v_cmp_gt_u32_e64 s[80:81], s2, v8
	v_add_u32_e32 v8, 0xf8a, v2
	v_lshlrev_b32_e32 v15, 1, v15
	v_cmp_gt_u32_e64 s[26:27], s2, v4
; __device__ __forceinline__ void toeplitz_item(const Params& p, int layer, int half, int c, bf16* sm, int dry, unsigned* done_ctr) {
;     ...
;   f16v acc[2][2];
; #pragma unroll
;   for (int mi = 0; mi < 2; ++mi)
; #pragma unroll
;     for (int ni = 0; ni < 2; ++ni)
; #pragma unroll
;       for (int e = 0; e < 16; ++e) acc[mi][ni][e] = 0.f;
;   const int nbatch = (2 * nb) >> 2;
;   const int aq = (8 - (r & 7)) & 7;
;   const int rt = (r + 7) >> 3;
;   bf16 wreg[3];
;   {
;     const int m0 = OFF - 128 * (-nb + 3) - 128;
; #pragma unroll
;     for (int i = 0; i < 3; ++i) { int x = tid + 256 * i; wreg[i] = x < 648 ? rho[m0 + x] : (bf16)0; }
;   }
;   for (int bt = 0; bt < nbatch; ++bt) {
;     const int D0 = -nb + 4 * bt;
;     __syncthreads();
; #pragma unroll
;     for (int i = 0; i < 3; ++i) {
;       const int x = tid + 256 * i;
;       if (x < 648) {
; #pragma unroll
;         for (int qq = 0; qq < 8; ++qq) {
;           const int y = x - qq;
;           if (y >= 0 && (y >> 3) < 80) sW[(qq * 83 + (y >> 3)) * 8 + (y & 7)] = wreg[i];
;         }
;       }
;     }
;     __syncthreads();
;     if (bt + 1 < nbatch) {
;       const int m0 = OFF - 128 * (D0 + 4 + 3) - 128;
; #pragma unroll
;       for (int i = 0; i < 3; ++i) { int x = tid + 256 * i; wreg[i] = x < 648 ? rho[m0 + x] : (bf16)0; }
;     }
;     for (int Dl = 0; Dl < 4; ++Dl) {
;       const int D = D0 + Dl;
;       bool actv[2];
;       int bblk[2];
; #pragma unroll
;       for (int ni = 0; ni < 2; ++ni) {
;         const int nlo = 32 * wn + 64 * ni;
;         actv[ni] = half ? true : !((nlo + 31 - D < 0) || (nlo - D >= 128));
;         const int n = nlo + r;
;         const int src = n - D;
;         const bool valid = half ? ((unsigned)((n & 15) - D) < 16u) : ((unsigned)src < 128u);
;         bblk[ni] = valid ? src : 128;
;       }
;       if (!actv[0] && !actv[1]) continue;
;       const int tb = 16 * (3 - Dl) + 16 + hh - rt;
;       const bf16* ap0 = sW + (aq * 83 + tb - 4 * (2 * wm)) * 8;
;       const bf16* bp0 = sU + bblk[0] * 136 + 8 * hh;
;       const bf16* bp1 = sU + bblk[1] * 136 + 8 * hh;
	v_add_u32_e32 v4, 0x108a, v2
	v_and_b32_e32 v3, 0x3ff8, v3
	v_add_u32_e32 v16, 1, v2
	v_and_b32_e32 v8, 0x1ff8, v8
	v_and_b32_e32 v4, 0x3ff8, v4
	v_lshl_or_b32 v112, v3, 1, v15
	v_add_u32_e32 v3, 0x1f9, v2
	v_and_b32_e32 v16, 7, v16
	v_lshl_or_b32 v128, v8, 1, v15
	v_add_u32_e32 v8, -7, v2
	v_lshl_or_b32 v120, v4, 1, v15
	v_add_u32_e32 v4, 0xf9, v2
	v_cmp_gt_u32_e64 s[64:65], s2, v3
	v_add_u32_e32 v3, 0x1421, v2
	v_ashrrev_i32_e32 v104, 7, v2
	v_lshlrev_b32_e32 v0, 5, v0
	v_cmp_gt_u32_e64 s[58:59], s2, v2
	v_cmp_gt_u32_e64 s[78:79], s2, v8
	v_lshlrev_b32_e32 v16, 1, v16
	v_cmp_gt_u32_e64 s[24:25], s2, v4
	v_and_b32_e32 v3, 0x3ff8, v3
	s_movk_i32 s2, 0x60
	v_lshlrev_b32_e32 v60, 2, v6
	v_mov_b32_e32 v61, 0x5d959d10
	v_lshrrev_b32_e32 v60, v60, v61
	v_and_b32_e32 v60, 15, v60
	v_and_b32_e32 v107, 32, v0
	v_add_u32_e32 v8, 0x1221, v2
	v_add_u32_e32 v4, 0x1321, v2
	v_lshl_or_b32 v111, v3, 1, v16
	v_or_b32_e32 v138, 0xffffffc0, v0
	v_mad_u32_u24 v0, v6, s2, v103
	v_add_u32_e32 v0, v0, v60
	v_lshl_or_b32 v3, v104, 3, v7
	v_and_b32_e32 v17, 0x3f8, v2
	v_and_b32_e32 v8, 0x17f8, v8
	v_and_b32_e32 v4, 0x3ff8, v4
	v_sub_u32_e32 v0, v0, v3
	v_mov_b32_e32 v3, 0x400
	v_mov_b32_e32 v14, v1
	v_mov_b32_e32 v15, v1
	v_lshl_or_b32 v134, v17, 1, v12
	v_lshl_or_b32 v127, v8, 1, v16
	v_lshl_or_b32 v119, v4, 1, v16
	v_writelane_b32 v255, s20, 24
	v_lshl_add_u32 v108, v0, 4, v3
	v_or_b32_e32 v105, v107, v5
	v_add_u32_e32 v100, 0x7d00, v2
	v_mov_b32_e32 v0, v1
	v_mov_b32_e32 v2, v1
	v_mov_b32_e32 v3, v1
	v_mov_b32_e32 v4, v1
	v_mov_b32_e32 v5, v1
	v_mov_b32_e32 v6, v1
	v_mov_b32_e32 v7, v1
	v_mov_b32_e32 v8, v1
	v_mov_b32_e32 v9, v1
	v_mov_b32_e32 v10, v1
	v_mov_b32_e32 v11, v1
	v_mov_b32_e32 v12, v1
	v_mov_b32_e32 v13, v1
	v_mov_b64_e32 v[30:31], v[14:15]
	v_mov_b64_e32 v[46:47], v[14:15]
	v_mov_b64_e32 v[62:63], v[14:15]
	v_mov_b64_e32 v[78:79], v[14:15]
	s_mov_b32 s0, 0
	v_lshlrev_b32_e32 v106, 4, v103
	v_writelane_b32 v255, s21, 25
	v_or_b32_e32 v136, 31, v107
	v_or_b32_e32 v137, 0xffffff80, v107
	v_or_b32_e32 v109, 0x5f, v107
	s_mov_b32 s74, 0
	v_mov_b64_e32 v[28:29], v[12:13]
	v_mov_b64_e32 v[26:27], v[10:11]
	v_mov_b64_e32 v[24:25], v[8:9]
	v_mov_b64_e32 v[22:23], v[6:7]
	v_mov_b64_e32 v[20:21], v[4:5]
	v_mov_b64_e32 v[18:19], v[2:3]
	v_mov_b64_e32 v[16:17], v[0:1]
	v_mov_b64_e32 v[44:45], v[12:13]
	v_mov_b64_e32 v[42:43], v[10:11]
	v_mov_b64_e32 v[40:41], v[8:9]
	v_mov_b64_e32 v[38:39], v[6:7]
	v_mov_b64_e32 v[36:37], v[4:5]
	v_mov_b64_e32 v[34:35], v[2:3]
	v_mov_b64_e32 v[32:33], v[0:1]
	v_mov_b64_e32 v[60:61], v[12:13]
	v_mov_b64_e32 v[58:59], v[10:11]
	v_mov_b64_e32 v[56:57], v[8:9]
	v_mov_b64_e32 v[54:55], v[6:7]
	v_mov_b64_e32 v[52:53], v[4:5]
	v_mov_b64_e32 v[50:51], v[2:3]
	v_mov_b64_e32 v[48:49], v[0:1]
	v_mov_b64_e32 v[76:77], v[12:13]
	v_mov_b64_e32 v[74:75], v[10:11]
	v_mov_b64_e32 v[72:73], v[8:9]
	v_mov_b64_e32 v[70:71], v[6:7]
	v_mov_b64_e32 v[68:69], v[4:5]
	v_mov_b64_e32 v[66:67], v[2:3]
	v_mov_b64_e32 v[64:65], v[0:1]
	v_add_u32_e32 v133, 224, v133
	v_add_u32_e32 v132, 624, v132
	v_add_u32_e32 v131, 768, v131
	v_add_u32_e32 v130, 912, v130
	v_add_u32_e32 v129, 1184, v129
	v_add_u32_e32 v128, 1456, v128
	v_add_u32_e32 v127, 1536, v127
	v_add_u32_e32 v125, 224, v125
	v_add_u32_e32 v124, 624, v124
	v_add_u32_e32 v123, 768, v123
	v_add_u32_e32 v122, 912, v122
	v_add_u32_e32 v121, 1184, v121
	v_add_u32_e32 v120, 1456, v120
	v_add_u32_e32 v119, 1536, v119
	v_add_u32_e32 v117, 224, v117
	v_add_u32_e32 v116, 624, v116
	v_add_u32_e32 v115, 768, v115
	v_add_u32_e32 v114, 912, v114
	v_add_u32_e32 v113, 1184, v113
	v_add_u32_e32 v112, 1456, v112
	v_add_u32_e32 v111, 1536, v111
	s_branch .LBB0_1371
